# MLA attention fast unmasked tile body, diff-attention output tail with hoisted gain loads and dwordx4 stores, static wave priority in attention
# speedup vs baseline: 1.0434x; 1.0172x over previous
; DI int ltid() { int t = threadIdx.x; asm volatile("" : "+v"(t)); return t; }
; __global__ void __launch_bounds__(NTHR) mega_fwd(Params p) {
;     ...
;         float lam;
;         const float lam_init = 0.8f - 0.6f * expf(-0.3f * (float)l);
;         {
;           const int lane = ltid() & 63;
;           const float* lv = p.in[8] + l * 256;
;           float sa = lv[lane] * lv[64 + lane], sb = lv[128 + lane] * lv[192 + lane];
; #pragma unroll
;           for (int m = 32; m >= 1; m >>= 1) { sa += __shfl_xor(sa, m); sb += __shfl_xor(sb, m); }
;           lam = expf(sa) - expf(sb) + lam_init;
;         }
;         const float L2E = 1.4426950408889634f;
; #pragma unroll 1
;         for (int it = 0; it < ((G == 256) ? 16 : (4096 + G - 1) / G); ++it) {
.LBB0_11:
	v_cvt_f32_i32_e32 v0, s20
	s_mov_b32 s2, 0x3fb8aa3b
	v_readlane_b32 s6, v251, 6
	s_mov_b32 s3, 0xc2ce8ed0
	v_mul_f32_e32 v0, 0xbe99999a, v0
	v_mul_f32_e32 v2, 0x3fb8aa3b, v0
	v_fma_f32 v3, v0, s2, -v2
	v_rndne_f32_e32 v4, v2
	v_fmac_f32_e32 v3, 0x32a5705f, v0
	v_sub_f32_e32 v2, v2, v4
	v_add_f32_e32 v2, v2, v3
	v_exp_f32_e32 v2, v2
	v_cvt_i32_f32_e32 v3, v4
	v_readlane_b32 s7, v251, 7
	s_add_u32 s53, s6, 0x35800000
	v_cmp_ngt_f32_e32 vcc, s3, v0
	v_ldexp_f32 v2, v2, v3
	s_mov_b32 s4, 0x42b17218
	s_addc_u32 s54, s7, 0
	v_cndmask_b32_e32 v2, 0, v2, vcc
	v_cmp_nlt_f32_e32 vcc, s4, v0
	s_lshl_b32 s0, s20, 8
	s_ashr_i32 s1, s0, 31
	v_cndmask_b32_e32 v0, v197, v2, vcc
	v_mov_b32_e32 v2, v195
	s_lshl_b64 s[0:1], s[0:1], 2
	v_readlane_b32 s56, v252, 0
	v_and_b32_e32 v2, 63, v2
	v_readlane_b32 s57, v252, 1
	s_add_u32 s0, s56, s0
	s_addc_u32 s1, s57, s1
	v_lshlrev_b32_e32 v2, 2, v2
	global_load_dword v3, v2, s[0:1]
	global_load_dword v4, v2, s[0:1] offset:256
	global_load_dword v6, v2, s[0:1] offset:512
	s_nop 0
	global_load_dword v2, v2, s[0:1] offset:768
	v_cmp_lt_i32_e32 vcc, v200, v199
	s_lshl_b32 s0, s20, 7
	s_ashr_i32 s1, s0, 31
	v_cndmask_b32_e32 v8, v198, v200, vcc
	v_lshlrev_b32_e32 v156, 2, v8
	v_cmp_lt_i32_e32 vcc, v201, v199
	v_readlane_b32 s58, v252, 2
	s_lshl_b64 s[0:1], s[0:1], 2
	v_readlane_b32 s59, v252, 3
	s_add_u32 s14, s58, s0
	s_addc_u32 s15, s59, s1
	s_add_u32 s56, s6, 0x35800180
	v_fmamk_f32 v0, v0, 0xbf19999a, v196
	s_addc_u32 s57, s7, 0
	s_add_u32 s58, s6, 0x18000180
	s_mov_b32 s55, 0
	v_sub_f32_e32 v157, 1.0, v0
	s_addc_u32 s59, s7, 0
	v_readlane_b32 s60, v252, 4
	v_readlane_b32 s61, v252, 5
	v_readlane_b32 s62, v252, 6
	v_readlane_b32 s63, v252, 7
	v_readlane_b32 s64, v252, 8
	v_readlane_b32 s65, v252, 9
	v_readlane_b32 s66, v252, 10
	v_readlane_b32 s67, v252, 11
	v_readlane_b32 s68, v252, 12
	v_readlane_b32 s69, v252, 13
	v_readlane_b32 s70, v252, 14
	v_readlane_b32 s71, v252, 15
	s_waitcnt vmcnt(0)
	v_mul_f32_e32 v5, v3, v4
	ds_bpermute_b32 v5, v156, v5
	s_waitcnt vmcnt(0)
	v_mul_f32_e32 v7, v6, v2
	s_waitcnt lgkmcnt(0)
	v_fmac_f32_e32 v5, v3, v4
	ds_bpermute_b32 v3, v156, v7
	s_waitcnt lgkmcnt(0)
	v_fmac_f32_e32 v3, v6, v2
	v_cndmask_b32_e32 v2, v198, v201, vcc
	v_lshlrev_b32_e32 v2, 2, v2
	ds_bpermute_b32 v4, v2, v5
	ds_bpermute_b32 v2, v2, v3
	v_cmp_lt_i32_e32 vcc, v202, v199
	s_waitcnt lgkmcnt(1)
	v_add_f32_e32 v4, v5, v4
	s_waitcnt lgkmcnt(0)
	v_add_f32_e32 v2, v3, v2
	v_cndmask_b32_e32 v3, v198, v202, vcc
	v_lshlrev_b32_e32 v3, 2, v3
	ds_bpermute_b32 v5, v3, v4
	ds_bpermute_b32 v3, v3, v2
	v_cmp_lt_i32_e32 vcc, v203, v199
	s_waitcnt lgkmcnt(1)
	v_add_f32_e32 v4, v4, v5
	s_waitcnt lgkmcnt(0)
	v_add_f32_e32 v2, v2, v3
	v_cndmask_b32_e32 v3, v198, v203, vcc
	v_lshlrev_b32_e32 v3, 2, v3
	ds_bpermute_b32 v5, v3, v4
	ds_bpermute_b32 v3, v3, v2
	v_cmp_lt_i32_e32 vcc, v204, v199
	s_waitcnt lgkmcnt(1)
	v_add_f32_e32 v4, v4, v5
	s_waitcnt lgkmcnt(0)
	v_add_f32_e32 v2, v2, v3
	v_cndmask_b32_e32 v3, v198, v204, vcc
	v_lshlrev_b32_e32 v3, 2, v3
	ds_bpermute_b32 v5, v3, v4
	ds_bpermute_b32 v3, v3, v2
	v_cmp_lt_i32_e32 vcc, v205, v199
	s_waitcnt lgkmcnt(1)
	v_add_f32_e32 v4, v4, v5
	s_waitcnt lgkmcnt(0)
	v_add_f32_e32 v2, v2, v3
	v_cndmask_b32_e32 v3, v198, v205, vcc
	v_lshlrev_b32_e32 v3, 2, v3
	ds_bpermute_b32 v5, v3, v4
	ds_bpermute_b32 v3, v3, v2
	s_waitcnt lgkmcnt(1)
	v_add_f32_e32 v4, v4, v5
	s_waitcnt lgkmcnt(0)
	v_add_f32_e32 v2, v2, v3
	v_mul_f32_e32 v3, 0x3fb8aa3b, v4
	v_fma_f32 v5, v4, s2, -v3
	v_rndne_f32_e32 v6, v3
	v_fmac_f32_e32 v5, 0x32a5705f, v4
	v_sub_f32_e32 v3, v3, v6
	v_add_f32_e32 v3, v3, v5
	v_exp_f32_e32 v3, v3
	v_cvt_i32_f32_e32 v5, v6
	v_cmp_ngt_f32_e32 vcc, s3, v4
	v_ldexp_f32 v3, v3, v5
	s_nop 0
	v_cndmask_b32_e32 v3, 0, v3, vcc
	v_cmp_nlt_f32_e32 vcc, s4, v4
	v_mul_f32_e32 v4, 0x3fb8aa3b, v2
	v_fma_f32 v5, v2, s2, -v4
	v_rndne_f32_e32 v6, v4
	v_fmac_f32_e32 v5, 0x32a5705f, v2
	v_sub_f32_e32 v4, v4, v6
	v_add_f32_e32 v4, v4, v5
	v_exp_f32_e32 v4, v4
	v_cvt_i32_f32_e32 v5, v6
	v_cndmask_b32_e32 v3, v197, v3, vcc
	v_cmp_ngt_f32_e32 vcc, s3, v2
	v_ldexp_f32 v4, v4, v5
	s_nop 0
	v_cndmask_b32_e32 v4, 0, v4, vcc
	v_cmp_nlt_f32_e32 vcc, s4, v2
	s_nop 1
	v_cndmask_b32_e32 v2, v197, v4, vcc
	v_sub_f32_e32 v2, v3, v2
	v_add_f32_e32 v150, v0, v2
	v_mov_b32_e32 v151, v150
	v_readfirstlane_b32 s100, v195
	s_nop 3
	s_lshr_b32 s100, s100, 8
	s_cmp_eq_u32 s100, 1
	s_cbranch_scc0 .Lmy_noprio
	s_setprio 1
.Lmy_noprio:
	s_branch .LBB0_14
.LBB0_12:
	s_add_i32 s55, s55, 1
	s_mov_b64 s[0:1], 0

; DI unsigned pack2(float a, float b) { fl2_t f = {a, b}; bf2_t r = __builtin_convertvector(f, bf2_t); return __builtin_bit_cast(unsigned, r); }
; template <int DK, int DV, int NM, bool CAUSAL> ...
;     ...
;   asm volatile("s_waitcnt lgkmcnt(0)" ::: "memory");
;   __builtin_amdgcn_s_barrier();
;   const float l_tot = lacc[0];
;   const float inv = 1.f / l_tot;
; #pragma unroll
;   for (int d = 0; d < NDVB; ++d)
; #pragma unroll
;     for (int i = 0; i < 16; ++i) o[d][i] *= inv;
;     ...
;   if (NM == 1 || wave < 4) {
;     bf16_t* op = O + (size_t)(wq * 32 + l31) * ldo + 4 * h;
; #pragma unroll
;     for (int d = 0; d < NDVB; ++d)
; #pragma unroll
;       for (int g = 0; g < 4; ++g) {
;         f4 gg = {1.f, 1.f, 1.f, 1.f};
;         if (NM == 2) gg = *(const f4*)(og + d * 32 + 8 * g + 4 * h);
;         u2 u;
;         u.x = pack2(o[d][4 * g + 0] * rn_out * gg.x, o[d][4 * g + 1] * rn_out * gg.y);
;         u.y = pack2(o[d][4 * g + 2] * rn_out * gg.z, o[d][4 * g + 3] * rn_out * gg.w);
;         *(u2*)(op + d * 32 + 8 * g) = u;
;       }
.LBB0_35:
	s_or_b64 exec, exec, s[6:7]
	v_add_f32_e32 v248, v248, v249
	s_nop 0
	v_mov_b32_e32 v249, v248
	s_nop 1
	v_permlane32_swap_b32 v249, v248
	v_add_f32_e32 v248, v248, v249
	v_add_f32_e32 v48, v48, v248
	s_nop 0
	v_div_scale_f32 v0, s[4:5], v48, v48, 1.0
	v_rcp_f32_e32 v2, v0
	s_waitcnt lgkmcnt(0)
	s_barrier
	s_mov_b64 s[8:9], 0
	v_fma_f32 v3, -v0, v2, 1.0
	v_fmac_f32_e32 v2, v3, v2
	v_div_scale_f32 v3, vcc, 1.0, v48, 1.0
	v_mul_f32_e32 v4, v3, v2
	v_fma_f32 v5, -v0, v4, v3
	v_fmac_f32_e32 v4, v5, v2
	v_fma_f32 v0, -v0, v4, v3
	v_div_fmas_f32 v0, v0, v2, v4
	v_div_fixup_f32 v0, v0, v48, 1.0
	v_pk_mul_f32 v[2:3], v[32:33], v[0:1] op_sel_hi:[1,0]
	v_pk_mul_f32 v[4:5], v[34:35], v[0:1] op_sel_hi:[1,0]
	v_pk_mul_f32 v[6:7], v[36:37], v[0:1] op_sel_hi:[1,0]
	v_pk_mul_f32 v[8:9], v[38:39], v[0:1] op_sel_hi:[1,0]
	v_pk_mul_f32 v[10:11], v[40:41], v[0:1] op_sel_hi:[1,0]
	v_pk_mul_f32 v[12:13], v[42:43], v[0:1] op_sel_hi:[1,0]
	v_pk_mul_f32 v[14:15], v[44:45], v[0:1] op_sel_hi:[1,0]
	v_pk_mul_f32 v[32:33], v[46:47], v[0:1] op_sel_hi:[1,0]
	v_pk_mul_f32 v[16:17], v[16:17], v[0:1] op_sel_hi:[1,0]
	v_pk_mul_f32 v[18:19], v[18:19], v[0:1] op_sel_hi:[1,0]
	v_pk_mul_f32 v[20:21], v[20:21], v[0:1] op_sel_hi:[1,0]
	v_pk_mul_f32 v[22:23], v[22:23], v[0:1] op_sel_hi:[1,0]
	v_pk_mul_f32 v[24:25], v[24:25], v[0:1] op_sel_hi:[1,0]
	v_pk_mul_f32 v[26:27], v[26:27], v[0:1] op_sel_hi:[1,0]
	v_pk_mul_f32 v[28:29], v[28:29], v[0:1] op_sel_hi:[1,0]
	v_pk_mul_f32 v[30:31], v[30:31], v[0:1] op_sel_hi:[1,0]
	v_lshlrev_b32_e32 v0, 1, v130
	v_lshl_add_u64 v[34:35], v[120:121], 0, v[0:1]
	v_cvt_pk_bf16_f32 v2, v2, v3
	v_cvt_pk_bf16_f32 v3, v4, v5
	flat_store_dwordx2 v[34:35], v[2:3]
	v_cvt_pk_bf16_f32 v2, v6, v7
	v_cvt_pk_bf16_f32 v3, v8, v9
	flat_store_dwordx2 v[34:35], v[2:3] offset:16
	v_cvt_pk_bf16_f32 v2, v10, v11
	v_cvt_pk_bf16_f32 v3, v12, v13
	flat_store_dwordx2 v[34:35], v[2:3] offset:32
	v_cvt_pk_bf16_f32 v2, v14, v15
	v_cvt_pk_bf16_f32 v3, v32, v33
	flat_store_dwordx2 v[34:35], v[2:3] offset:48
	v_cvt_pk_bf16_f32 v2, v16, v17
	v_cvt_pk_bf16_f32 v3, v18, v19
	flat_store_dwordx2 v[34:35], v[2:3] offset:64
	v_cvt_pk_bf16_f32 v2, v20, v21
	v_cvt_pk_bf16_f32 v3, v22, v23
	flat_store_dwordx2 v[34:35], v[2:3] offset:80
	v_cvt_pk_bf16_f32 v2, v24, v25
	v_cvt_pk_bf16_f32 v3, v26, v27
	flat_store_dwordx2 v[34:35], v[2:3] offset:96
	v_cvt_pk_bf16_f32 v2, v28, v29
	v_cvt_pk_bf16_f32 v3, v30, v31
	s_and_b64 vcc, exec, s[18:19]
	flat_store_dwordx2 v[34:35], v[2:3] offset:112
	s_cbranch_vccnz .LBB0_84

; DI int ltid() { int t = threadIdx.x; asm volatile("" : "+v"(t)); return t; }
; template <int DK, int DV, int NM, bool CAUSAL> ...
;     ...
;   const int tid = ltid(), lane = tid & 63, wave = tid >> 6, h = lane >> 5, l31 = lane & 31;
;   const int wq = (NM == 2) ? (wave & 3) : wave;
;   const int mymap = (NM == 2) ? (wave >> 2) : 0;
;   const int q0w = q0 + wq * 32;
;   bf16x8 qf[NKC16];
;   f32x16 o[NDVB];
; #pragma unroll
;   for (int d = 0; d < NDVB; ++d)
; #pragma unroll
;     for (int i = 0; i < 16; ++i) o[d][i] = 0.f;
;   f32x16 lacc;
; #pragma unroll
;   for (int i = 0; i < 16; ++i) lacc[i] = 0.f;
;   u4 onesu; onesu.x = onesu.y = onesu.z = onesu.w = 0x3F803F80u;
;   const bf16x8 ones = __builtin_bit_cast(bf16x8, onesu);
;   const int wu = __builtin_amdgcn_readfirstlane(wave);
;   const int krow = lane >> 4, kslot = lane & 15;
;   const int vrow = lane >> 3, vslot = lane & 7;
;   auto issue = [&](int kt) {
;     char* st = smem + (kt & 3) * STAGE;
; #pragma unroll
;     for (int i = 0; i < 2; ++i) {
;       const int r = (wu * 2 + i) * 4 + krow;
;       const int c = kslot ^ (r & 15);
;       if (KCHV == 16 || c < KCHV)
;         __builtin_amdgcn_global_load_lds((const unsigned*)(Kg + (size_t)(kt * 64 + r) * ldk + c * 8), (unsigned*)(st + (wu * 2 + i) * 1024), 16, 0, 0);
;     }
; #pragma unroll
;     for (int i = 0; i < NVI; ++i) {
;       const int d = (wu * NVI + i) * 8 + vrow;
;       const int c = vslot ^ ((d >> 1) & 7);
;       __builtin_amdgcn_global_load_lds((const unsigned*)(Vt + (size_t)d * ldv + kt * 64 + c * 8), (unsigned*)(st + KBYTES + (wu * NVI + i) * 1024), 16, 0, 0);
;     }
;   };
;   asm volatile("s_waitcnt vmcnt(0)" ::: "memory");
;   __syncthreads();
;   if (0 < nkt) issue(0);
;   if (1 < nkt) issue(1);
;   if (2 < nkt) issue(2);
;   {
;     const bf16_t* qp = Q + (size_t)(wq * 32 + l31) * ldq + mymap * DK + h * 8;
; #pragma unroll
;     for (int kc = 0; kc < NKC16; ++kc) qf[kc] = *(const bf16x8*)(qp + kc * 16);
; #pragma unroll
;     for (int kc = 0; kc < NKC16; ++kc) asm volatile("" : "+v"(qf[kc]));
;   }
.LBB0_50:
	s_or_b64 exec, exec, s[18:19]
	s_xor_b64 s[18:19], s[8:9], -1
	s_and_b64 s[8:9], s[8:9], exec
	s_cselect_b32 s65, s35, s34
	s_or_b32 s8, s65, s61
	s_mul_hi_u32 s9, s8, 0x600
	s_mulk_i32 s8, 0x600
	s_add_u32 s8, s62, s8
	s_addc_u32 s9, s63, s9
	v_lshlrev_b32_e32 v22, 5, v9
	v_and_b32_e32 v23, 31, v6
	v_lshrrev_b32_e32 v19, 5, v10
	v_or_b32_e32 v0, v22, v23
	v_mov_b64_e32 v[2:3], s[8:9]
	v_mad_i64_i32 v[120:121], s[8:9], v0, s33, v[2:3]
	v_lshlrev_b32_e32 v0, 4, v19
	v_lshl_add_u64 v[2:3], v[120:121], 0, v[0:1]
	flat_load_dwordx4 v[116:119], v[2:3]
	flat_load_dwordx4 v[112:115], v[2:3] offset:32
	flat_load_dwordx4 v[108:111], v[2:3] offset:64
	flat_load_dwordx4 v[104:107], v[2:3] offset:96
	flat_load_dwordx4 v[100:103], v[2:3] offset:128
	flat_load_dwordx4 v[96:99], v[2:3] offset:160
	v_lshl_add_u64 v[2:3], v[122:123], 0, s[94:95]
	s_add_i32 m0, s64, 0x10000
	v_mov_b32_e32 v17, v1
	global_load_lds_dwordx4 v[2:3], off
	v_bfe_u32 v21, v6, 1, 3
	v_add_u32_e32 v20, s31, v8
	v_lshl_add_u64 v[126:127], s[0:1], 0, v[16:17]
	v_bitop3_b32 v16, v19, v21, 2 bitop3:0x36
	v_bitop3_b32 v17, v19, v21, 4 bitop3:0x36
	v_bitop3_b32 v25, v19, v21, 6 bitop3:0x36
	v_ashrrev_i32_e32 v21, 31, v20
	v_lshrrev_b32_e32 v0, 1, v6
	v_and_b32_e32 v24, 7, v7
	v_lshlrev_b32_e32 v134, 4, v16
	v_lshlrev_b32_e32 v132, 4, v17
	v_lshlrev_b64 v[16:17], 12, v[20:21]
	v_mov_b32_e32 v14, v1
	v_mov_b32_e32 v15, v1
	v_bitop3_b32 v0, v0, v19, 7 bitop3:0x6c
	v_xor_b32_e32 v26, v19, v18
	v_bitop3_b32 v27, v19, v18, 2 bitop3:0x36
	v_bitop3_b32 v28, v19, v18, 4 bitop3:0x36
	v_bitop3_b32 v29, v19, v18, 6 bitop3:0x36
	v_bitop3_b32 v30, v19, v18, 8 bitop3:0x36
	v_bitop3_b32 v18, v19, v18, 10 bitop3:0x36
	v_add_u32_e32 v140, s65, v22
	v_lshl_or_b32 v16, v24, 4, v16
	s_add_i32 s8, s65, 0x100
	v_lshl_add_u64 v[124:125], v[4:5], 1, s[0:1]
	v_mov_b32_e32 v2, v1
	v_mov_b32_e32 v3, v1
	v_mov_b32_e32 v4, v1
	v_mov_b32_e32 v5, v1
	v_mov_b32_e32 v6, v1
	v_mov_b32_e32 v7, v1
	v_mov_b32_e32 v8, v1
	v_mov_b32_e32 v9, v1
	v_mov_b32_e32 v10, v1
	v_mov_b32_e32 v11, v1
	v_mov_b32_e32 v12, v1
	v_mov_b32_e32 v13, v1
	v_lshlrev_b32_e32 v144, 8, v23
	v_lshlrev_b32_e32 v139, 7, v23
	v_lshlrev_b32_e32 v130, 2, v19
	v_lshlrev_b32_e32 v135, 4, v0
	v_lshlrev_b32_e32 v131, 4, v25
	v_lshlrev_b32_e32 v147, 4, v26
	v_lshlrev_b32_e32 v146, 4, v27
	v_lshlrev_b32_e32 v145, 4, v28
	v_lshlrev_b32_e32 v143, 4, v29
	v_lshlrev_b32_e32 v142, 4, v30
	v_lshlrev_b32_e32 v141, 4, v18
	v_or_b32_e32 v133, v140, v23
	v_lshl_add_u64 v[128:129], s[16:17], 0, v[16:17]
	s_lshr_b32 s67, s8, 6
	v_mov_b32_e32 v0, v1
	v_mov_b64_e32 v[30:31], v[14:15]
	v_mov_b64_e32 v[46:47], v[14:15]
	v_mov_b64_e32 v[62:63], v[14:15]
	s_mov_b32 s68, 0
	v_or_b32_e32 v148, 31, v140
	s_lshl_b32 s65, s30, 11
	s_add_i32 s66, s67, -2
	v_mov_b64_e32 v[28:29], v[12:13]
	v_mov_b64_e32 v[26:27], v[10:11]
	v_mov_b64_e32 v[24:25], v[8:9]
	v_mov_b64_e32 v[22:23], v[6:7]
	v_mov_b64_e32 v[20:21], v[4:5]
	v_mov_b64_e32 v[18:19], v[2:3]
	v_mov_b64_e32 v[16:17], v[0:1]
	v_mov_b64_e32 v[44:45], v[12:13]
	v_mov_b64_e32 v[42:43], v[10:11]
	v_mov_b64_e32 v[40:41], v[8:9]
	v_mov_b64_e32 v[38:39], v[6:7]
	v_mov_b64_e32 v[36:37], v[4:5]
	v_mov_b64_e32 v[34:35], v[2:3]
	v_mov_b64_e32 v[32:33], v[0:1]
	s_mov_b32 s69, 0
	v_mov_b64_e32 v[60:61], v[12:13]
	v_mov_b64_e32 v[58:59], v[10:11]
	v_mov_b64_e32 v[56:57], v[8:9]
	v_mov_b64_e32 v[54:55], v[6:7]
	v_mov_b64_e32 v[52:53], v[4:5]
	v_mov_b64_e32 v[50:51], v[2:3]
	v_mov_b64_e32 v[48:49], v[0:1]
	v_mov_b32_e32 v248, v1
	v_mov_b32_e32 v249, v1
	v_readfirstlane_b32 s101, v140
	s_waitcnt vmcnt(0) lgkmcnt(0)
	s_branch .LBB0_52

; #define MFMA(a, b, c) __builtin_amdgcn_mfma_f32_32x32x16_bf16((a), (b), (c), 0, 0, 0)
; DI unsigned pack2(float a, float b) { fl2_t f = {a, b}; bf2_t r = __builtin_convertvector(f, bf2_t); return __builtin_bit_cast(unsigned, r); }
; DI int crow(int i, int h) { return (i & 3) + 8 * (i >> 2) + 4 * h; }
; template <int DK, int DV, int NM, bool CAUSAL> ...
;     ...
;     const bool skip = CAUSAL && (kt * 64 > q0w + 31);
;     if (!skip) {
;       const char* base = smem + (kt & 3) * STAGE;
;       f32x16 s[2];
; #pragma unroll
;       for (int sb = 0; sb < 2; ++sb) {
; #pragma unroll
;         for (int i = 0; i < 16; ++i) s[sb][i] = 0.f;
;         const char* pk = base + (sb * 32 + l31) * 256;
; #pragma unroll
;         for (int kc = 0; kc < NKC16; ++kc) {
;           const bf16x8 a = *(const bf16x8*)(pk + (((mymap * (DK / 8) + kc * 2 + h) ^ (l31 & 15)) * 16));
;           s[sb] = MFMA(a, qf[kc], s[sb]);
;         }
;         __builtin_amdgcn_sched_barrier(0);
;       }
;       const bool need_mask = CAUSAL && (kt * 64 + 63 > q0w);
;       const char* pv = base + KBYTES + l31 * 128;
;       const int vsw = (l31 >> 1) & 7;
;       bf16x8 pf[4];
;       auto expo = [&](int sb) {
; #pragma unroll
;         for (int i = 0; i < 16; ++i) {
;           float pz = __builtin_amdgcn_exp2f(s[sb][i]);
;           if (need_mask) {
;             const int key = kt * 64 + sb * 32 + crow(i, h);
;             if (key > q0w + l31) pz = 0.f;
;           }
;           s[sb][i] = pz;
;         }
; #pragma unroll
;         for (int k2 = 0; k2 < 2; ++k2) {
;           u4 pu;
;           pu.x = pack2(s[sb][k2 * 8 + 0], s[sb][k2 * 8 + 1]);
;           pu.y = pack2(s[sb][k2 * 8 + 2], s[sb][k2 * 8 + 3]);
;           pu.z = pack2(s[sb][k2 * 8 + 4], s[sb][k2 * 8 + 5]);
;           pu.w = pack2(s[sb][k2 * 8 + 6], s[sb][k2 * 8 + 7]);
;           pf[sb * 2 + k2] = __builtin_bit_cast(bf16x8, pu);
;         }
;       };
;       auto pvmm = [&](int ks) {
;         lacc = MFMA(ones, pf[ks], lacc);
; #pragma unroll
;         for (int d = 0; d < NDVB; ++d) {
;           const u4 au = *(const u4*)(pv + d * 32 * 128 + (((ks * 2 + h) ^ vsw) * 16));
;           o[d] = MFMA(__builtin_bit_cast(bf16x8, au), pf[ks], o[d]);
;         }
;       };
;       expo(0);
;       pvmm(0); pvmm(1);
;       expo(1);
;       pvmm(2); pvmm(3);
;       __builtin_amdgcn_sched_barrier(0);
.LBB0_58:
	s_add_i32 s8, s68, 63
	s_cmp_le_i32 s8, s101
	s_cbranch_scc0 .Lmy_mslow
	s_and_b32 s8, s69, 3
	s_mulk_i32 s8, 0x6000
	v_or_b32_e32 v0, s8, v144
	v_add_u32_e32 v6, v0, v147
	v_add_u32_e32 v7, v0, v146
	v_add_u32_e32 v8, v0, v145
	v_add_u32_e32 v9, v0, v143
	v_add_u32_e32 v10, v0, v142
	v_add_u32_e32 v11, v0, v141
	ds_read_b128 v[212:215], v6
	ds_read_b128 v[216:219], v7
	ds_read_b128 v[220:223], v8
	ds_read_b128 v[224:227], v9
	ds_read_b128 v[228:231], v10
	ds_read_b128 v[232:235], v11
	v_or_b32_e32 v0, s8, v139
	v_add_u32_e32 v12, v0, v135
	v_add_u32_e32 v13, v0, v134
	v_add_u32_e32 v14, v0, v132
	v_add_u32_e32 v15, v0, v131
	ds_read_b128 v[236:239], v12 offset:16384
	ds_read_b128 v[240:243], v12 offset:20480
	s_waitcnt lgkmcnt(7)
	v_mfma_f32_32x32x16_bf16 v[80:95], v[212:215], v[116:119], 0
	ds_read_b128 v[212:215], v6 offset:8192
	s_waitcnt lgkmcnt(7)
	v_mfma_f32_32x32x16_bf16 v[80:95], v[216:219], v[112:115], v[80:95]
	ds_read_b128 v[216:219], v7 offset:8192
	s_waitcnt lgkmcnt(7)
	v_mfma_f32_32x32x16_bf16 v[80:95], v[220:223], v[108:111], v[80:95]
	ds_read_b128 v[220:223], v8 offset:8192
	s_waitcnt lgkmcnt(7)
	v_mfma_f32_32x32x16_bf16 v[80:95], v[224:227], v[104:107], v[80:95]
	ds_read_b128 v[224:227], v9 offset:8192
	s_waitcnt lgkmcnt(7)
	v_mfma_f32_32x32x16_bf16 v[80:95], v[228:231], v[100:103], v[80:95]
	ds_read_b128 v[228:231], v10 offset:8192
	s_waitcnt lgkmcnt(7)
	v_mfma_f32_32x32x16_bf16 v[80:95], v[232:235], v[96:99], v[80:95]
	ds_read_b128 v[232:235], v11 offset:8192
	s_waitcnt lgkmcnt(5)
	v_mfma_f32_32x32x16_bf16 v[64:79], v[212:215], v[116:119], 0
	ds_read_b128 v[212:215], v13 offset:16384
	s_waitcnt lgkmcnt(5)
	v_mfma_f32_32x32x16_bf16 v[64:79], v[216:219], v[112:115], v[64:79]
	ds_read_b128 v[216:219], v13 offset:20480
	s_waitcnt lgkmcnt(5)
	v_mfma_f32_32x32x16_bf16 v[64:79], v[220:223], v[108:111], v[64:79]
	ds_read_b128 v[220:223], v14 offset:16384
	s_waitcnt lgkmcnt(5)
	v_mfma_f32_32x32x16_bf16 v[64:79], v[224:227], v[104:107], v[64:79]
	ds_read_b128 v[224:227], v14 offset:20480
	s_waitcnt lgkmcnt(5)
	v_mfma_f32_32x32x16_bf16 v[64:79], v[228:231], v[100:103], v[64:79]
	ds_read_b128 v[228:231], v15 offset:16384
	s_waitcnt lgkmcnt(5)
	v_mfma_f32_32x32x16_bf16 v[64:79], v[232:235], v[96:99], v[64:79]
	ds_read_b128 v[232:235], v15 offset:20480
	v_exp_f32_e32 v80, v80
	v_exp_f32_e32 v81, v81
	v_exp_f32_e32 v82, v82
	v_exp_f32_e32 v83, v83
	v_exp_f32_e32 v84, v84
	v_exp_f32_e32 v85, v85
	v_exp_f32_e32 v86, v86
	v_exp_f32_e32 v87, v87
	v_add_f32_e32 v248, v248, v80
	v_add_f32_e32 v249, v249, v81
	v_add_f32_e32 v248, v248, v82
	v_add_f32_e32 v249, v249, v83
	v_add_f32_e32 v248, v248, v84
	v_add_f32_e32 v249, v249, v85
	v_add_f32_e32 v248, v248, v86
	v_add_f32_e32 v249, v249, v87
	v_cvt_pk_bf16_f32 v186, v80, v81
	v_cvt_pk_bf16_f32 v187, v82, v83
	v_cvt_pk_bf16_f32 v188, v84, v85
	v_cvt_pk_bf16_f32 v189, v86, v87
	s_nop 0
	v_mfma_f32_32x32x16_bf16 v[32:47], v[236:239], v[186:189], v[32:47]
	v_exp_f32_e32 v88, v88
	v_exp_f32_e32 v89, v89
	v_exp_f32_e32 v90, v90
	v_exp_f32_e32 v91, v91
	v_exp_f32_e32 v92, v92
	v_exp_f32_e32 v93, v93
	v_mfma_f32_32x32x16_bf16 v[16:31], v[240:243], v[186:189], v[16:31]
	v_exp_f32_e32 v94, v94
	v_exp_f32_e32 v95, v95
	v_add_f32_e32 v248, v248, v88
	v_add_f32_e32 v249, v249, v89
	v_add_f32_e32 v248, v248, v90
	v_add_f32_e32 v249, v249, v91
	v_add_f32_e32 v248, v248, v92
	v_add_f32_e32 v249, v249, v93
	v_add_f32_e32 v248, v248, v94
	v_add_f32_e32 v249, v249, v95
	v_cvt_pk_bf16_f32 v190, v88, v89
	v_cvt_pk_bf16_f32 v191, v90, v91
	v_cvt_pk_bf16_f32 v192, v92, v93
	v_cvt_pk_bf16_f32 v193, v94, v95
	s_nop 0
	s_waitcnt lgkmcnt(5)
	v_mfma_f32_32x32x16_bf16 v[32:47], v[212:215], v[190:193], v[32:47]
	v_exp_f32_e32 v64, v64
	v_exp_f32_e32 v65, v65
	v_exp_f32_e32 v66, v66
	v_exp_f32_e32 v67, v67
	v_exp_f32_e32 v68, v68
	v_exp_f32_e32 v69, v69
	s_waitcnt lgkmcnt(4)
	v_mfma_f32_32x32x16_bf16 v[16:31], v[216:219], v[190:193], v[16:31]
	v_exp_f32_e32 v70, v70
	v_exp_f32_e32 v71, v71
	v_add_f32_e32 v248, v248, v64
	v_add_f32_e32 v249, v249, v65
	v_add_f32_e32 v248, v248, v66
	v_add_f32_e32 v249, v249, v67
	v_add_f32_e32 v248, v248, v68
	v_add_f32_e32 v249, v249, v69
	v_add_f32_e32 v248, v248, v70
	v_add_f32_e32 v249, v249, v71
	v_cvt_pk_bf16_f32 v244, v64, v65
	v_cvt_pk_bf16_f32 v245, v66, v67
	v_cvt_pk_bf16_f32 v246, v68, v69
	v_cvt_pk_bf16_f32 v247, v70, v71
	s_nop 0
	s_waitcnt lgkmcnt(3)
	v_mfma_f32_32x32x16_bf16 v[32:47], v[220:223], v[244:247], v[32:47]
	v_exp_f32_e32 v72, v72
	v_exp_f32_e32 v73, v73
	v_exp_f32_e32 v74, v74
	v_exp_f32_e32 v75, v75
	v_exp_f32_e32 v76, v76
	v_exp_f32_e32 v77, v77
	s_waitcnt lgkmcnt(2)
	v_mfma_f32_32x32x16_bf16 v[16:31], v[224:227], v[244:247], v[16:31]
	v_exp_f32_e32 v78, v78
	v_exp_f32_e32 v79, v79
	v_add_f32_e32 v248, v248, v72
	v_add_f32_e32 v249, v249, v73
	v_add_f32_e32 v248, v248, v74
	v_add_f32_e32 v249, v249, v75
	v_add_f32_e32 v248, v248, v76
	v_add_f32_e32 v249, v249, v77
	v_add_f32_e32 v248, v248, v78
	v_add_f32_e32 v249, v249, v79
	v_cvt_pk_bf16_f32 v2, v72, v73
	v_cvt_pk_bf16_f32 v3, v74, v75
	v_cvt_pk_bf16_f32 v4, v76, v77
	v_cvt_pk_bf16_f32 v5, v78, v79
	s_nop 0
	s_waitcnt lgkmcnt(1)
	v_mfma_f32_32x32x16_bf16 v[32:47], v[228:231], v[2:5], v[32:47]
	s_waitcnt lgkmcnt(0)
	v_mfma_f32_32x32x16_bf16 v[16:31], v[232:235], v[2:5], v[16:31]
	s_branch .LBB0_51

; template <int DK, int DV, int NM, bool CAUSAL> ...
;     ...
;     __syncthreads();
;     if (wave < 4) {
;       float ss = 0.f;
; #pragma unroll
;       for (int d = 0; d < NDVB; ++d) {
; #pragma unroll
;         for (int i = 0; i < 16; ++i) {
;           const float v = o[d][i] - lam * buf[(d * 16 + i) * 256 + wave * 64 + lane];
;           o[d][i] = v;
;           ss += v * v;
;         }
;         __builtin_amdgcn_sched_barrier(0);
;       }
;       ss += __shfl_xor(ss, 32);
.LBB0_104:
	s_or_b64 exec, exec, s[4:5]
	v_cmp_gt_i32_e32 vcc, 4, v159
	s_waitcnt vmcnt(0) lgkmcnt(0)
	s_barrier
	s_and_saveexec_b64 s[4:5], vcc
	s_cbranch_execz .LBB0_87
	v_lshlrev_b32_e32 v0, 2, v158
	ds_read2st64_b32 v[18:19], v0 offset1:4
	ds_read2st64_b32 v[20:21], v0 offset0:8 offset1:12
	ds_read2st64_b32 v[22:23], v0 offset0:16 offset1:20
	ds_read2st64_b32 v[24:25], v0 offset0:24 offset1:28
	ds_read2st64_b32 v[26:27], v0 offset0:32 offset1:36
	ds_read2st64_b32 v[28:29], v0 offset0:40 offset1:44
	ds_read2st64_b32 v[30:31], v0 offset0:48 offset1:52
	ds_read2st64_b32 v[34:35], v0 offset0:56 offset1:60
	ds_read2st64_b32 v[36:37], v0 offset0:64 offset1:68
	ds_read2st64_b32 v[42:43], v0 offset0:72 offset1:76
	ds_read2st64_b32 v[46:47], v0 offset0:80 offset1:84
	ds_read2st64_b32 v[62:63], v0 offset0:88 offset1:92
	ds_read2st64_b32 v[98:99], v0 offset0:96 offset1:100
	ds_read2st64_b32 v[100:101], v0 offset0:104 offset1:108
	ds_read2st64_b32 v[102:103], v0 offset0:112 offset1:116
	ds_read2st64_b32 v[104:105], v0 offset0:120 offset1:124
	ds_read2st64_b32 v[106:107], v0 offset0:128 offset1:132
	ds_read2st64_b32 v[108:109], v0 offset0:136 offset1:140
	ds_read2st64_b32 v[110:111], v0 offset0:144 offset1:148
	ds_read2st64_b32 v[112:113], v0 offset0:152 offset1:156
	ds_read2st64_b32 v[114:115], v0 offset0:160 offset1:164
	ds_read2st64_b32 v[116:117], v0 offset0:168 offset1:172
	ds_read2st64_b32 v[118:119], v0 offset0:176 offset1:180
	ds_read2st64_b32 v[120:121], v0 offset0:184 offset1:188
	ds_read2st64_b32 v[122:123], v0 offset0:192 offset1:196
	ds_read2st64_b32 v[124:125], v0 offset0:200 offset1:204
	ds_read2st64_b32 v[126:127], v0 offset0:208 offset1:212
	ds_read2st64_b32 v[6:7], v0 offset0:240 offset1:244
	ds_read2st64_b32 v[128:129], v0 offset0:216 offset1:220
	ds_read2st64_b32 v[92:93], v0 offset0:248 offset1:252
	ds_read2st64_b32 v[130:131], v0 offset0:224 offset1:228
	ds_read2st64_b32 v[132:133], v0 offset0:232 offset1:236
	s_waitcnt lgkmcnt(4)
	v_pk_fma_f32 v[6:7], v[150:151], v[6:7], v[4:5] neg_lo:[1,0,0] neg_hi:[1,0,0]
	s_waitcnt lgkmcnt(2)
	v_pk_fma_f32 v[4:5], v[150:151], v[92:93], v[2:3] neg_lo:[1,0,0] neg_hi:[1,0,0]
	v_pk_mul_f32 v[134:135], v[6:7], v[6:7]
	v_pk_mul_f32 v[136:137], v[4:5], v[4:5]
	v_pk_fma_f32 v[84:85], v[150:151], v[18:19], v[84:85] neg_lo:[1,0,0] neg_hi:[1,0,0]
	v_lshlrev_b32_e32 v0, 1, v160
	v_lshlrev_b32_e32 v92, 2, v160
	v_pk_fma_f32 v[90:91], v[150:151], v[20:21], v[90:91] neg_lo:[1,0,0] neg_hi:[1,0,0]
	v_pk_mul_f32 v[140:141], v[84:85], v[84:85]
	v_lshl_add_u64 v[2:3], v[144:145], 0, v[0:1]
	global_load_dwordx4 v[94:97], v92, s[14:15]
	v_pk_mul_f32 v[138:139], v[90:91], v[90:91]
	v_add_f32_e32 v0, v140, v141
	v_pk_fma_f32 v[82:83], v[150:151], v[22:23], v[82:83] neg_lo:[1,0,0] neg_hi:[1,0,0]
	v_add_f32_e32 v0, v0, v138
	v_pk_mul_f32 v[144:145], v[82:83], v[82:83]
	v_add_f32_e32 v0, v0, v139
	v_pk_fma_f32 v[88:89], v[150:151], v[24:25], v[88:89] neg_lo:[1,0,0] neg_hi:[1,0,0]
	v_add_f32_e32 v0, v0, v144
	v_pk_mul_f32 v[142:143], v[88:89], v[88:89]
	v_add_f32_e32 v0, v0, v145
	v_pk_fma_f32 v[80:81], v[150:151], v[26:27], v[80:81] neg_lo:[1,0,0] neg_hi:[1,0,0]
	v_add_f32_e32 v0, v0, v142
	v_pk_mul_f32 v[148:149], v[80:81], v[80:81]
	v_add_f32_e32 v0, v0, v143
	v_pk_fma_f32 v[86:87], v[150:151], v[28:29], v[86:87] neg_lo:[1,0,0] neg_hi:[1,0,0]
	v_add_f32_e32 v0, v0, v148
	v_pk_mul_f32 v[146:147], v[86:87], v[86:87]
	v_add_f32_e32 v0, v0, v149
	v_pk_fma_f32 v[154:155], v[150:151], v[30:31], v[72:73] neg_lo:[1,0,0] neg_hi:[1,0,0]
	v_add_f32_e32 v0, v0, v146
	v_pk_mul_f32 v[158:159], v[154:155], v[154:155]
	v_add_f32_e32 v0, v0, v147
	v_pk_fma_f32 v[78:79], v[150:151], v[34:35], v[78:79] neg_lo:[1,0,0] neg_hi:[1,0,0]
	v_add_f32_e32 v0, v0, v158
	v_pk_mul_f32 v[152:153], v[78:79], v[78:79]
	v_add_f32_e32 v0, v0, v159
	v_pk_fma_f32 v[160:161], v[150:151], v[36:37], v[68:69] neg_lo:[1,0,0] neg_hi:[1,0,0]
	v_add_f32_e32 v0, v0, v152
	v_pk_mul_f32 v[162:163], v[160:161], v[160:161]
	v_add_f32_e32 v0, v0, v153
	v_pk_fma_f32 v[72:73], v[150:151], v[42:43], v[76:77] neg_lo:[1,0,0] neg_hi:[1,0,0]
	v_add_f32_e32 v0, v0, v162
	v_pk_mul_f32 v[76:77], v[72:73], v[72:73]
	v_add_f32_e32 v0, v0, v163
	v_pk_fma_f32 v[66:67], v[150:151], v[46:47], v[66:67] neg_lo:[1,0,0] neg_hi:[1,0,0]
	v_add_f32_e32 v0, v0, v76
	v_pk_mul_f32 v[164:165], v[66:67], v[66:67]
	v_add_f32_e32 v0, v0, v77
	v_pk_fma_f32 v[68:69], v[150:151], v[62:63], v[74:75] neg_lo:[1,0,0] neg_hi:[1,0,0]
	v_add_f32_e32 v0, v0, v164
	v_pk_mul_f32 v[74:75], v[68:69], v[68:69]
	v_add_f32_e32 v0, v0, v165
	v_pk_fma_f32 v[62:63], v[150:151], v[98:99], v[64:65] neg_lo:[1,0,0] neg_hi:[1,0,0]
	v_add_f32_e32 v0, v0, v74
	v_pk_mul_f32 v[64:65], v[62:63], v[62:63]
	v_add_f32_e32 v0, v0, v75
	v_pk_fma_f32 v[46:47], v[150:151], v[100:101], v[70:71] neg_lo:[1,0,0] neg_hi:[1,0,0]
	v_add_f32_e32 v0, v0, v64
	v_pk_mul_f32 v[70:71], v[46:47], v[46:47]
	v_add_f32_e32 v0, v0, v65
	v_pk_fma_f32 v[42:43], v[150:151], v[102:103], v[56:57] neg_lo:[1,0,0] neg_hi:[1,0,0]
	v_add_f32_e32 v0, v0, v70
	v_pk_mul_f32 v[56:57], v[42:43], v[42:43]
	v_add_f32_e32 v0, v0, v71
	v_pk_fma_f32 v[36:37], v[150:151], v[104:105], v[60:61] neg_lo:[1,0,0] neg_hi:[1,0,0]
	v_add_f32_e32 v0, v0, v56
	v_pk_mul_f32 v[60:61], v[36:37], v[36:37]
	v_add_f32_e32 v0, v0, v57
	v_pk_fma_f32 v[34:35], v[150:151], v[106:107], v[52:53] neg_lo:[1,0,0] neg_hi:[1,0,0]
	v_add_f32_e32 v0, v0, v60
	v_pk_mul_f32 v[52:53], v[34:35], v[34:35]
	v_add_f32_e32 v0, v0, v61
	v_pk_fma_f32 v[32:33], v[150:151], v[108:109], v[32:33] neg_lo:[1,0,0] neg_hi:[1,0,0]
	v_add_f32_e32 v0, v0, v52
	v_pk_mul_f32 v[98:99], v[32:33], v[32:33]
; DI unsigned pack2(float a, float b) { fl2_t f = {a, b}; bf2_t r = __builtin_convertvector(f, bf2_t); return __builtin_bit_cast(unsigned, r); }
; template <int DK, int DV, int NM, bool CAUSAL> ...
;     ...
;       ss += __shfl_xor(ss, 32);
;       rn_out = rsqrtf(ss * (1.f / DV) + EPSV) * omul;
;     }
;   }
;   if (NM == 1 || wave < 4) {
;     bf16_t* op = O + (size_t)(wq * 32 + l31) * ldo + 4 * h;
; #pragma unroll
;     for (int d = 0; d < NDVB; ++d)
; #pragma unroll
;       for (int g = 0; g < 4; ++g) {
;         f4 gg = {1.f, 1.f, 1.f, 1.f};
;         if (NM == 2) gg = *(const f4*)(og + d * 32 + 8 * g + 4 * h);
;         u2 u;
;         u.x = pack2(o[d][4 * g + 0] * rn_out * gg.x, o[d][4 * g + 1] * rn_out * gg.y);
;         u.y = pack2(o[d][4 * g + 2] * rn_out * gg.z, o[d][4 * g + 3] * rn_out * gg.w);
;         *(u2*)(op + d * 32 + 8 * g) = u;
;       }
	v_add_f32_e32 v0, v0, v53
	v_pk_fma_f32 v[30:31], v[150:151], v[110:111], v[50:51] neg_lo:[1,0,0] neg_hi:[1,0,0]
	v_add_f32_e32 v0, v0, v98
	v_pk_mul_f32 v[50:51], v[30:31], v[30:31]
	v_add_f32_e32 v0, v0, v99
	v_pk_fma_f32 v[28:29], v[150:151], v[112:113], v[58:59] neg_lo:[1,0,0] neg_hi:[1,0,0]
	v_add_f32_e32 v0, v0, v50
	v_pk_mul_f32 v[58:59], v[28:29], v[28:29]
	v_add_f32_e32 v0, v0, v51
	v_pk_fma_f32 v[26:27], v[150:151], v[114:115], v[48:49] neg_lo:[1,0,0] neg_hi:[1,0,0]
	v_add_f32_e32 v0, v0, v58
	v_pk_mul_f32 v[48:49], v[26:27], v[26:27]
	v_add_f32_e32 v0, v0, v59
	v_pk_fma_f32 v[24:25], v[150:151], v[116:117], v[54:55] neg_lo:[1,0,0] neg_hi:[1,0,0]
	v_add_f32_e32 v0, v0, v48
	v_pk_mul_f32 v[54:55], v[24:25], v[24:25]
	v_add_f32_e32 v0, v0, v49
	v_pk_fma_f32 v[22:23], v[150:151], v[118:119], v[14:15] neg_lo:[1,0,0] neg_hi:[1,0,0]
	v_add_f32_e32 v0, v0, v54
	v_pk_mul_f32 v[100:101], v[22:23], v[22:23]
	v_add_f32_e32 v0, v0, v55
	v_pk_fma_f32 v[20:21], v[150:151], v[120:121], v[44:45] neg_lo:[1,0,0] neg_hi:[1,0,0]
	v_add_f32_e32 v0, v0, v100
	v_pk_mul_f32 v[44:45], v[20:21], v[20:21]
	v_add_f32_e32 v0, v0, v101
	v_pk_fma_f32 v[18:19], v[150:151], v[122:123], v[12:13] neg_lo:[1,0,0] neg_hi:[1,0,0]
	v_add_f32_e32 v0, v0, v44
	v_pk_mul_f32 v[104:105], v[18:19], v[18:19]
	v_add_f32_e32 v0, v0, v45
	v_pk_fma_f32 v[16:17], v[150:151], v[124:125], v[16:17] neg_lo:[1,0,0] neg_hi:[1,0,0]
	v_add_f32_e32 v0, v0, v104
	v_pk_mul_f32 v[102:103], v[16:17], v[16:17]
	v_add_f32_e32 v0, v0, v105
	v_pk_fma_f32 v[14:15], v[150:151], v[126:127], v[8:9] neg_lo:[1,0,0] neg_hi:[1,0,0]
	v_add_f32_e32 v0, v0, v102
	v_pk_mul_f32 v[106:107], v[14:15], v[14:15]
	v_add_f32_e32 v0, v0, v103
	v_pk_fma_f32 v[12:13], v[150:151], v[128:129], v[40:41] neg_lo:[1,0,0] neg_hi:[1,0,0]
	v_add_f32_e32 v0, v0, v106
	v_pk_mul_f32 v[40:41], v[12:13], v[12:13]
	v_add_f32_e32 v0, v0, v107
	s_waitcnt lgkmcnt(1)
	v_pk_fma_f32 v[10:11], v[150:151], v[130:131], v[10:11] neg_lo:[1,0,0] neg_hi:[1,0,0]
	v_add_f32_e32 v0, v0, v40
	v_pk_mul_f32 v[108:109], v[10:11], v[10:11]
	v_add_f32_e32 v0, v0, v41
	s_waitcnt lgkmcnt(0)
	v_pk_fma_f32 v[8:9], v[150:151], v[132:133], v[38:39] neg_lo:[1,0,0] neg_hi:[1,0,0]
	v_add_f32_e32 v0, v0, v108
	v_pk_mul_f32 v[38:39], v[8:9], v[8:9]
	v_add_f32_e32 v0, v0, v109
	v_add_f32_e32 v0, v0, v38
	v_add_f32_e32 v0, v0, v39
	v_add_f32_e32 v0, v0, v134
	v_add_f32_e32 v0, v0, v135
	v_add_f32_e32 v0, v0, v136
	v_add_f32_e32 v0, v0, v137
	ds_bpermute_b32 v38, v156, v0
	s_waitcnt lgkmcnt(0)
	v_add_f32_e32 v0, v0, v38
	v_fmamk_f32 v0, v0, 0x3c000000, v194
	v_cmp_gt_f32_e32 vcc, s96, v0
	v_mul_f32_e32 v38, 0x4b800000, v0
	s_nop 0
	v_cndmask_b32_e32 v0, v0, v38, vcc
	v_rsq_f32_e32 v0, v0
	s_nop 0
	v_mul_f32_e32 v38, 0x45800000, v0
	v_cndmask_b32_e32 v0, v0, v38, vcc
	v_mul_f32_e32 v0, v157, v0
	global_load_dwordx4 v[212:215], v92, s[14:15] offset:32
	global_load_dwordx4 v[216:219], v92, s[14:15] offset:64
	global_load_dwordx4 v[220:223], v92, s[14:15] offset:96
	global_load_dwordx4 v[224:227], v92, s[14:15] offset:128
	global_load_dwordx4 v[228:231], v92, s[14:15] offset:160
	global_load_dwordx4 v[232:235], v92, s[14:15] offset:192
	global_load_dwordx4 v[236:239], v92, s[14:15] offset:224
	global_load_dwordx4 v[240:243], v92, s[14:15] offset:256
	global_load_dwordx4 v[244:247], v92, s[14:15] offset:288
	global_load_dwordx4 v[186:189], v92, s[14:15] offset:320
	global_load_dwordx4 v[190:193], v92, s[14:15] offset:352
	global_load_dwordx4 v[98:101], v92, s[14:15] offset:384
	global_load_dwordx4 v[102:105], v92, s[14:15] offset:416
	global_load_dwordx4 v[106:109], v92, s[14:15] offset:448
	global_load_dwordx4 v[110:113], v92, s[14:15] offset:480
	v_and_b32_e32 v126, 32, v198
	v_lshrrev_b32_e32 v126, 2, v126
	v_mov_b32_e32 v127, v1
	v_lshl_add_u64 v[126:127], v[2:3], 0, v[126:127]
	v_pk_mul_f32 v[84:85], v[84:85], v[0:1] op_sel_hi:[1,0]
	v_pk_mul_f32 v[90:91], v[90:91], v[0:1] op_sel_hi:[1,0]
	v_pk_mul_f32 v[82:83], v[82:83], v[0:1] op_sel_hi:[1,0]
	v_pk_mul_f32 v[88:89], v[88:89], v[0:1] op_sel_hi:[1,0]
	v_pk_mul_f32 v[80:81], v[80:81], v[0:1] op_sel_hi:[1,0]
	v_pk_mul_f32 v[86:87], v[86:87], v[0:1] op_sel_hi:[1,0]
	v_pk_mul_f32 v[154:155], v[154:155], v[0:1] op_sel_hi:[1,0]
	v_pk_mul_f32 v[78:79], v[78:79], v[0:1] op_sel_hi:[1,0]
	v_pk_mul_f32 v[160:161], v[160:161], v[0:1] op_sel_hi:[1,0]
	v_pk_mul_f32 v[72:73], v[72:73], v[0:1] op_sel_hi:[1,0]
	v_pk_mul_f32 v[66:67], v[66:67], v[0:1] op_sel_hi:[1,0]
	v_pk_mul_f32 v[68:69], v[68:69], v[0:1] op_sel_hi:[1,0]
	v_pk_mul_f32 v[62:63], v[62:63], v[0:1] op_sel_hi:[1,0]
	v_pk_mul_f32 v[46:47], v[46:47], v[0:1] op_sel_hi:[1,0]
	v_pk_mul_f32 v[42:43], v[42:43], v[0:1] op_sel_hi:[1,0]
	v_pk_mul_f32 v[36:37], v[36:37], v[0:1] op_sel_hi:[1,0]
	v_pk_mul_f32 v[34:35], v[34:35], v[0:1] op_sel_hi:[1,0]
	v_pk_mul_f32 v[32:33], v[32:33], v[0:1] op_sel_hi:[1,0]
	v_pk_mul_f32 v[30:31], v[30:31], v[0:1] op_sel_hi:[1,0]
	v_pk_mul_f32 v[28:29], v[28:29], v[0:1] op_sel_hi:[1,0]
	v_pk_mul_f32 v[26:27], v[26:27], v[0:1] op_sel_hi:[1,0]
	v_pk_mul_f32 v[24:25], v[24:25], v[0:1] op_sel_hi:[1,0]
	v_pk_mul_f32 v[22:23], v[22:23], v[0:1] op_sel_hi:[1,0]
	v_pk_mul_f32 v[20:21], v[20:21], v[0:1] op_sel_hi:[1,0]
	v_pk_mul_f32 v[18:19], v[18:19], v[0:1] op_sel_hi:[1,0]
	v_pk_mul_f32 v[16:17], v[16:17], v[0:1] op_sel_hi:[1,0]
	v_pk_mul_f32 v[14:15], v[14:15], v[0:1] op_sel_hi:[1,0]
	v_pk_mul_f32 v[12:13], v[12:13], v[0:1] op_sel_hi:[1,0]
	v_pk_mul_f32 v[10:11], v[10:11], v[0:1] op_sel_hi:[1,0]
	v_pk_mul_f32 v[8:9], v[8:9], v[0:1] op_sel_hi:[1,0]
	v_pk_mul_f32 v[6:7], v[6:7], v[0:1] op_sel_hi:[1,0]
	v_pk_mul_f32 v[4:5], v[4:5], v[0:1] op_sel_hi:[1,0]
	s_waitcnt vmcnt(0)
; DI unsigned pack2(float a, float b) { fl2_t f = {a, b}; bf2_t r = __builtin_convertvector(f, bf2_t); return __builtin_bit_cast(unsigned, r); }
; template <int DK, int DV, int NM, bool CAUSAL> ...
;     ...
;     bf16_t* op = O + (size_t)(wq * 32 + l31) * ldo + 4 * h;
; #pragma unroll
;     for (int d = 0; d < NDVB; ++d)
; #pragma unroll
;       for (int g = 0; g < 4; ++g) {
;         f4 gg = {1.f, 1.f, 1.f, 1.f};
;         if (NM == 2) gg = *(const f4*)(og + d * 32 + 8 * g + 4 * h);
;         u2 u;
;         u.x = pack2(o[d][4 * g + 0] * rn_out * gg.x, o[d][4 * g + 1] * rn_out * gg.y);
;         u.y = pack2(o[d][4 * g + 2] * rn_out * gg.z, o[d][4 * g + 3] * rn_out * gg.w);
;         *(u2*)(op + d * 32 + 8 * g) = u;
;       }
	v_pk_mul_f32 v[84:85], v[94:95], v[84:85]
	v_pk_mul_f32 v[90:91], v[96:97], v[90:91]
	v_pk_mul_f32 v[82:83], v[212:213], v[82:83]
	v_pk_mul_f32 v[88:89], v[214:215], v[88:89]
	v_cvt_pk_bf16_f32 v114, v84, v85
	v_cvt_pk_bf16_f32 v115, v90, v91
	v_cvt_pk_bf16_f32 v116, v82, v83
	v_cvt_pk_bf16_f32 v117, v88, v89
	s_nop 1
	v_permlane32_swap_b32 v114, v116
	v_permlane32_swap_b32 v115, v117
	flat_store_dwordx4 v[126:127], v[114:117]
	v_pk_mul_f32 v[80:81], v[216:217], v[80:81]
	v_pk_mul_f32 v[86:87], v[218:219], v[86:87]
	v_pk_mul_f32 v[154:155], v[220:221], v[154:155]
	v_pk_mul_f32 v[78:79], v[222:223], v[78:79]
	v_cvt_pk_bf16_f32 v118, v80, v81
	v_cvt_pk_bf16_f32 v119, v86, v87
	v_cvt_pk_bf16_f32 v120, v154, v155
	v_cvt_pk_bf16_f32 v121, v78, v79
	s_nop 1
	v_permlane32_swap_b32 v118, v120
	v_permlane32_swap_b32 v119, v121
	flat_store_dwordx4 v[126:127], v[118:121] offset:32
	v_pk_mul_f32 v[160:161], v[224:225], v[160:161]
	v_pk_mul_f32 v[72:73], v[226:227], v[72:73]
	v_pk_mul_f32 v[66:67], v[228:229], v[66:67]
	v_pk_mul_f32 v[68:69], v[230:231], v[68:69]
	v_cvt_pk_bf16_f32 v122, v160, v161
	v_cvt_pk_bf16_f32 v123, v72, v73
	v_cvt_pk_bf16_f32 v124, v66, v67
	v_cvt_pk_bf16_f32 v125, v68, v69
	s_nop 1
	v_permlane32_swap_b32 v122, v124
	v_permlane32_swap_b32 v123, v125
	flat_store_dwordx4 v[126:127], v[122:125] offset:64
	v_pk_mul_f32 v[62:63], v[232:233], v[62:63]
	v_pk_mul_f32 v[46:47], v[234:235], v[46:47]
	v_pk_mul_f32 v[42:43], v[236:237], v[42:43]
	v_pk_mul_f32 v[36:37], v[238:239], v[36:37]
	v_cvt_pk_bf16_f32 v114, v62, v63
	v_cvt_pk_bf16_f32 v115, v46, v47
	v_cvt_pk_bf16_f32 v116, v42, v43
	v_cvt_pk_bf16_f32 v117, v36, v37
	s_nop 1
	v_permlane32_swap_b32 v114, v116
	v_permlane32_swap_b32 v115, v117
	flat_store_dwordx4 v[126:127], v[114:117] offset:96
	v_pk_mul_f32 v[34:35], v[240:241], v[34:35]
	v_pk_mul_f32 v[32:33], v[242:243], v[32:33]
	v_pk_mul_f32 v[30:31], v[244:245], v[30:31]
	v_pk_mul_f32 v[28:29], v[246:247], v[28:29]
	v_cvt_pk_bf16_f32 v118, v34, v35
	v_cvt_pk_bf16_f32 v119, v32, v33
	v_cvt_pk_bf16_f32 v120, v30, v31
	v_cvt_pk_bf16_f32 v121, v28, v29
	s_nop 1
	v_permlane32_swap_b32 v118, v120
	v_permlane32_swap_b32 v119, v121
	flat_store_dwordx4 v[126:127], v[118:121] offset:128
	v_pk_mul_f32 v[26:27], v[186:187], v[26:27]
	v_pk_mul_f32 v[24:25], v[188:189], v[24:25]
	v_pk_mul_f32 v[22:23], v[190:191], v[22:23]
	v_pk_mul_f32 v[20:21], v[192:193], v[20:21]
	v_cvt_pk_bf16_f32 v122, v26, v27
	v_cvt_pk_bf16_f32 v123, v24, v25
	v_cvt_pk_bf16_f32 v124, v22, v23
	v_cvt_pk_bf16_f32 v125, v20, v21
	s_nop 1
	v_permlane32_swap_b32 v122, v124
	v_permlane32_swap_b32 v123, v125
	flat_store_dwordx4 v[126:127], v[122:125] offset:160
	v_pk_mul_f32 v[18:19], v[98:99], v[18:19]
	v_pk_mul_f32 v[16:17], v[100:101], v[16:17]
	v_pk_mul_f32 v[14:15], v[102:103], v[14:15]
	v_pk_mul_f32 v[12:13], v[104:105], v[12:13]
	v_cvt_pk_bf16_f32 v114, v18, v19
	v_cvt_pk_bf16_f32 v115, v16, v17
	v_cvt_pk_bf16_f32 v116, v14, v15
	v_cvt_pk_bf16_f32 v117, v12, v13
	s_nop 1
	v_permlane32_swap_b32 v114, v116
	v_permlane32_swap_b32 v115, v117
	flat_store_dwordx4 v[126:127], v[114:117] offset:192
	v_pk_mul_f32 v[10:11], v[106:107], v[10:11]
	v_pk_mul_f32 v[8:9], v[108:109], v[8:9]
	v_pk_mul_f32 v[6:7], v[110:111], v[6:7]
	v_pk_mul_f32 v[4:5], v[112:113], v[4:5]
	v_cvt_pk_bf16_f32 v118, v10, v11
	v_cvt_pk_bf16_f32 v119, v8, v9
	v_cvt_pk_bf16_f32 v120, v6, v7
	v_cvt_pk_bf16_f32 v121, v4, v5
	s_nop 1
	v_permlane32_swap_b32 v118, v120
	v_permlane32_swap_b32 v119, v121
	flat_store_dwordx4 v[126:127], v[118:121] offset:224
	s_branch .LBB0_87
